# v19 plus: norm weight/shift/scale loads of the sample-row path issued at the top of the iteration (one exposed round trip fewer on the norm phases' critical path)
# baseline (speedup 1.0000x reference)
; __device__ __forceinline__ unsigned cvt_pk_bf16(float lo, float hi) { unsigned r; asm volatile("v_cvt_pk_bf16_f32 %0, %1, %2" : "=v"(r) : "v"(lo), "v"(hi)); return r; }
; #define LAS __attribute__((address_space(3)))
; __device__ __forceinline__ f32x4 sample_row_coop(const Frame& F, h16* X, const float* PART, int srow, int nsplit, LAS float* red, float& rs) {
;     typedef _Float16 h16x4 __attribute__((ext_vector_type(4)));
;     const int c = F.wave * 256 + F.lane * 4; h16x4* xp = (h16x4*)(X + (size_t)(TP + srow) * D + c); f32x4 v = __builtin_convertvector(*xp, f32x4);
;     if (nsplit > 0) { f32x4 s[7];
; #pragma unroll
;         for (int ks = 0; ks < 7; ++ks) s[ks] = ks < nsplit ? *(const f32x4*)(PART + ((size_t)ks * 128 + srow) * D + c) : (f32x4){0.f, 0.f, 0.f, 0.f};
;         v += ((s[0] + s[1]) + (s[2] + s[3])) + ((s[4] + s[5]) + s[6]); *xp = __builtin_convertvector(v, h16x4); }
;     const float ss = wave_sum((v[0] * v[0] + v[1] * v[1]) + (v[2] * v[2] + v[3] * v[3]));
;     __syncthreads(); if (F.lane == 0) red[F.wave] = ss; __syncthreads();
;     rs = 1.0f / sqrtf((((red[0] + red[1]) + (red[2] + red[3])) + ((red[4] + red[5]) + (red[6] + red[7]))) * (1.0f / D) + EPS);
; __device__ __forceinline__ void phase_norm(const Frame& F, int l, int which, int nsplit) {
;     ...
;     for (int sr = F.vcu; sr < TS; sr += F.G) { float rs; const f32x4 v = sample_row_coop(F, X, PART, sr, nsplit, (LAS float*)(F.lds + 65536), rs);
;         const int c = F.wave * 256 + F.lane * 4; const float* mp = mbase + (size_t)(4 + sr) * MODLD; const f32x4 w = *(const f32x4*)(nw + c), sh = *(const f32x4*)(mp + c), sc = *(const f32x4*)(mp + D + c);
;         const f32x4 h = (v * rs) * w * (sc + 1.0f) + sh; u32x2 o; o.x = cvt_pk_bf16(h[0], h[1]); o.y = cvt_pk_bf16(h[2], h[3]); *(u32x2*)(H + (size_t)(TP + sr) * D + c) = o; }
.LBB0_379:
	s_or_b64 exec, exec, s[22:23]
	s_add_i32 s11, 0, 0x10000
	v_mov_b32_e32 v16, s11
	s_waitcnt lgkmcnt(0)
	s_barrier
	ds_read_b128 v[12:15], v16
	ds_read_b128 v[16:19], v16 offset:16
	s_add_i32 s11, s6, 4
	v_lshl_add_u64 v[4:5], v[4:5], 0, s[56:57]
	s_waitcnt lgkmcnt(1)
	v_mov_b32_e32 v20, v12
	s_waitcnt lgkmcnt(0)
	v_mov_b32_e32 v21, v16
	v_mov_b32_e32 v16, v13
	v_pk_add_f32 v[12:13], v[20:21], v[16:17]
	v_mov_b32_e32 v16, v14
	v_mov_b32_e32 v17, v18
	v_mov_b32_e32 v18, v15
	v_pk_add_f32 v[14:15], v[16:17], v[18:19]
	s_nop 0
	v_pk_add_f32 v[12:13], v[12:13], v[14:15]
	s_nop 0
	v_add_f32_e32 v12, v12, v13
	v_fmamk_f32 v12, v12, 0x3a000000, v215
	v_cmp_gt_f32_e32 vcc, s90, v12
	v_mul_f32_e32 v13, 0x4f800000, v12
	s_nop 0
	v_cndmask_b32_e32 v12, v12, v13, vcc
	v_sqrt_f32_e32 v13, v12
	s_nop 0
	v_add_u32_e32 v14, -1, v13
	v_fma_f32 v15, -v14, v13, v12
	v_cmp_ge_f32_e64 s[42:43], 0, v15
	v_add_u32_e32 v15, 1, v13
	s_nop 0
	v_cndmask_b32_e64 v14, v13, v14, s[42:43]
	v_fma_f32 v13, -v15, v13, v12
	v_cmp_lt_f32_e64 s[42:43], 0, v13
	s_nop 1
	v_cndmask_b32_e64 v13, v14, v15, s[42:43]
	v_mul_f32_e32 v14, 0x37800000, v13
	v_cndmask_b32_e32 v13, v13, v14, vcc
	v_cmp_class_f32_e32 vcc, v12, v216
	s_nop 1
	v_cndmask_b32_e32 v12, v13, v12, vcc
	v_div_scale_f32 v13, s[12:13], v12, v12, 1.0
	v_rcp_f32_e32 v14, v13
	s_mul_hi_i32 s13, s11, 0x48000
	s_mul_i32 s11, s11, 0x48000
	s_add_u32 s12, s54, s11
	v_fma_f32 v15, -v13, v14, 1.0
	v_fmac_f32_e32 v14, v15, v14
	v_div_scale_f32 v15, vcc, 1.0, v12, 1.0
	v_mul_f32_e32 v16, v15, v14
	v_fma_f32 v17, -v13, v16, v15
	v_fmac_f32_e32 v16, v17, v14
	s_addc_u32 s13, s55, s13
	v_fma_f32 v13, -v13, v16, v15
	v_lshl_add_u64 v[20:21], v[0:1], 2, s[12:13]
	v_div_fmas_f32 v13, v13, v14, v16
	v_add_co_u32_e32 v20, vcc, s89, v20
	v_div_fixup_f32 v24, v13, v12, 1.0
	s_nop 0
	v_addc_co_u32_e32 v21, vcc, 0, v21, vcc
	v_pk_mul_f32 v[8:9], v[8:9], v[24:25] op_sel_hi:[1,0]
	v_pk_mul_f32 v[10:11], v[10:11], v[24:25] op_sel_hi:[1,0]
	s_add_i32 s6, s6, s46
	s_cmpk_gt_i32 s6, 0x7f
	s_waitcnt vmcnt(1)
	v_pk_mul_f32 v[10:11], v[228:229], v[10:11]
	v_pk_mul_f32 v[8:9], v[230:231], v[8:9]
	s_waitcnt vmcnt(0)
	v_pk_add_f32 v[12:13], v[234:235], 1.0 op_sel_hi:[1,0]
	v_pk_add_f32 v[14:15], v[232:233], 1.0 op_sel_hi:[1,0]
	v_pk_fma_f32 v[8:9], v[12:13], v[8:9], v[226:227]
	v_pk_fma_f32 v[10:11], v[14:15], v[10:11], v[224:225]
	s_nop 0
	v_cvt_pk_bf16_f32 v10, v10, v11
	v_cvt_pk_bf16_f32 v11, v8, v9
	v_lshl_add_u64 v[8:9], s[26:27], 0, v[6:7]
	v_lshl_add_u64 v[6:7], v[6:7], 0, s[58:59]
	global_store_dwordx2 v[8:9], v[10:11], off
	s_cbranch_scc1 .LBB0_383
.LBB0_380:
	s_add_i32 s98, s6, 4
	s_mul_hi_i32 s99, s98, 0x48000
	s_mul_i32 s98, s98, 0x48000
	s_add_u32 s100, s54, s98
	s_addc_u32 s101, s55, s99
	v_lshl_add_u64 v[236:237], v[0:1], 2, s[100:101]
	global_load_dwordx4 v[224:227], v[236:237], off
	global_load_dwordx4 v[228:231], v[2:3], off
	s_add_u32 s100, s100, s89
	s_addc_u32 s101, s101, 0
	v_lshl_add_u64 v[238:239], v[0:1], 2, s[100:101]
	global_load_dwordx4 v[232:235], v[238:239], off
	v_add_co_u32_e32 v8, vcc, 0xffa00000, v4
	v_lshl_add_u64 v[102:103], s[36:37], 0, v[6:7]
	s_nop 0
	v_addc_co_u32_e32 v9, vcc, -1, v5, vcc
	v_add_co_u32_e32 v12, vcc, 0xffb00000, v4
	global_load_dwordx2 v[104:105], v[102:103], off
	s_nop 0
	v_addc_co_u32_e32 v13, vcc, -1, v5, vcc
	v_add_co_u32_e32 v16, vcc, 0xffc00000, v4
	global_load_dwordx4 v[8:11], v[8:9], off
	s_nop 0
	global_load_dwordx4 v[12:15], v[12:13], off
	v_addc_co_u32_e32 v17, vcc, -1, v5, vcc
	v_add_co_u32_e32 v20, vcc, 0xffd00000, v4
	s_waitcnt vmcnt(2)
	v_cvt_f32_f16_e32 v106, v104
	v_addc_co_u32_e32 v21, vcc, -1, v5, vcc
	v_add_co_u32_e32 v24, vcc, 0xffe00000, v4
	global_load_dwordx4 v[16:19], v[16:17], off
	s_nop 0
	global_load_dwordx4 v[20:23], v[20:21], off
	v_addc_co_u32_e32 v25, vcc, -1, v5, vcc
	v_add_co_u32_e32 v28, vcc, 0xfff00000, v4
	v_cvt_f32_f16_sdwa v107, v104 dst_sel:DWORD dst_unused:UNUSED_PAD src0_sel:WORD_1
	s_nop 0
	v_addc_co_u32_e32 v29, vcc, -1, v5, vcc
	global_load_dwordx4 v[24:27], v[24:25], off
	s_nop 0
	global_load_dwordx4 v[28:31], v[28:29], off
	s_nop 0
	global_load_dwordx4 v[98:101], v[4:5], off
	v_cvt_f32_f16_e32 v104, v105
	v_cvt_f32_f16_sdwa v105, v105 dst_sel:DWORD dst_unused:UNUSED_PAD src0_sel:WORD_1
	s_waitcnt vmcnt(5)
	v_pk_add_f32 v[10:11], v[10:11], v[14:15]
	v_pk_add_f32 v[8:9], v[8:9], v[12:13]
	s_waitcnt vmcnt(3)
	v_pk_add_f32 v[12:13], v[18:19], v[22:23]
	v_pk_add_f32 v[14:15], v[16:17], v[20:21]
	v_pk_add_f32 v[10:11], v[10:11], v[12:13]
	v_pk_add_f32 v[8:9], v[8:9], v[14:15]
	s_waitcnt vmcnt(1)
	v_pk_add_f32 v[12:13], v[26:27], v[30:31]
	v_pk_add_f32 v[14:15], v[24:25], v[28:29]
	s_waitcnt vmcnt(0)
	v_pk_add_f32 v[12:13], v[12:13], v[100:101]
	v_pk_add_f32 v[14:15], v[14:15], v[98:99]
	v_pk_add_f32 v[10:11], v[10:11], v[12:13]
	v_pk_add_f32 v[12:13], v[8:9], v[14:15]
	v_pk_add_f32 v[8:9], v[10:11], v[104:105]
	v_pk_add_f32 v[10:11], v[12:13], v[106:107]
	v_mul_f32_e32 v15, v9, v9
	v_mul_f32_e32 v14, v11, v11
	v_cvt_pk_f16_f32 v13, v8, v9
	v_cvt_pk_f16_f32 v12, v10, v11
	v_fmac_f32_e32 v14, v10, v10
	v_fmac_f32_e32 v15, v8, v8
	global_store_dwordx2 v[102:103], v[12:13], off
	v_add_f32_e32 v12, v14, v15
	s_waitcnt lgkmcnt(0)
	s_barrier
	v_add_f32_dpp v12, v12, v12 quad_perm:[1,0,3,2] row_mask:0xf bank_mask:0xf bound_ctrl:1
	s_nop 1
	v_add_f32_dpp v12, v12, v12 quad_perm:[2,3,0,1] row_mask:0xf bank_mask:0xf bound_ctrl:1
	s_nop 1
	v_add_f32_dpp v12, v12, v12 row_half_mirror row_mask:0xf bank_mask:0xf bound_ctrl:1
	s_nop 1
	v_add_f32_dpp v12, v12, v12 row_mirror row_mask:0xf bank_mask:0xf bound_ctrl:1
	s_nop 0
	v_readlane_b32 s42, v12, 0
	v_readlane_b32 s11, v12, 16
	v_readlane_b32 s43, v12, 32
	v_readlane_b32 s12, v12, 48
	s_and_saveexec_b64 s[22:23], s[40:41]
	s_cbranch_execz .LBB0_379
	v_mov_b32_e32 v12, s11
	v_mov_b32_e32 v13, s12
	v_pk_add_f32 v[12:13], s[42:43], v[12:13]
	v_readlane_b32 s11, v248, 6
	v_add_f32_e32 v12, v12, v13
	s_nop 0
	v_mov_b32_e32 v13, s11
	ds_write_b32 v13, v12
	s_branch .LBB0_379

; __device__ __forceinline__ unsigned cvt_pk_bf16(float lo, float hi) { unsigned r; asm volatile("v_cvt_pk_bf16_f32 %0, %1, %2" : "=v"(r) : "v"(lo), "v"(hi)); return r; }
; #define LAS __attribute__((address_space(3)))
; __device__ __forceinline__ f32x4 sample_row_coop(const Frame& F, h16* X, const float* PART, int srow, int nsplit, LAS float* red, float& rs) {
;     typedef _Float16 h16x4 __attribute__((ext_vector_type(4)));
;     const int c = F.wave * 256 + F.lane * 4; h16x4* xp = (h16x4*)(X + (size_t)(TP + srow) * D + c); f32x4 v = __builtin_convertvector(*xp, f32x4);
;     if (nsplit > 0) { f32x4 s[7];
; #pragma unroll
;         for (int ks = 0; ks < 7; ++ks) s[ks] = ks < nsplit ? *(const f32x4*)(PART + ((size_t)ks * 128 + srow) * D + c) : (f32x4){0.f, 0.f, 0.f, 0.f};
;         v += ((s[0] + s[1]) + (s[2] + s[3])) + ((s[4] + s[5]) + s[6]); *xp = __builtin_convertvector(v, h16x4); }
;     const float ss = wave_sum((v[0] * v[0] + v[1] * v[1]) + (v[2] * v[2] + v[3] * v[3]));
;     __syncthreads(); if (F.lane == 0) red[F.wave] = ss; __syncthreads();
;     rs = 1.0f / sqrtf((((red[0] + red[1]) + (red[2] + red[3])) + ((red[4] + red[5]) + (red[6] + red[7]))) * (1.0f / D) + EPS);
; __device__ __forceinline__ void phase_norm(const Frame& F, int l, int which, int nsplit) {
;     ...
;     for (int sr = F.vcu; sr < TS; sr += F.G) { float rs; const f32x4 v = sample_row_coop(F, X, PART, sr, nsplit, (LAS float*)(F.lds + 65536), rs);
;         const int c = F.wave * 256 + F.lane * 4; const float* mp = mbase + (size_t)(4 + sr) * MODLD; const f32x4 w = *(const f32x4*)(nw + c), sh = *(const f32x4*)(mp + c), sc = *(const f32x4*)(mp + D + c);
;         const f32x4 h = (v * rs) * w * (sc + 1.0f) + sh; u32x2 o; o.x = cvt_pk_bf16(h[0], h[1]); o.y = cvt_pk_bf16(h[2], h[3]); *(u32x2*)(H + (size_t)(TP + sr) * D + c) = o; }
.LBB0_2207:
	s_or_b64 exec, exec, s[42:43]
	s_add_i32 s11, 0, 0x10000
	v_mov_b32_e32 v4, s11
	s_waitcnt lgkmcnt(0)
	s_barrier
	ds_read_b128 v[0:3], v4
	ds_read_b128 v[4:7], v4 offset:16
	s_add_i32 s11, s6, 4
	s_mul_hi_i32 s12, s11, 0x48000
	s_mul_i32 s11, s11, 0x48000
	s_waitcnt lgkmcnt(1)
	v_mov_b32_e32 v8, v0
	s_waitcnt lgkmcnt(0)
	v_mov_b32_e32 v9, v4
	v_mov_b32_e32 v4, v1
	v_pk_add_f32 v[0:1], v[8:9], v[4:5]
	v_mov_b32_e32 v4, v2
	v_mov_b32_e32 v5, v6
	v_mov_b32_e32 v6, v3
	v_pk_add_f32 v[2:3], v[4:5], v[6:7]
	v_lshl_add_u64 v[98:99], v[98:99], 0, s[70:71]
	v_pk_add_f32 v[0:1], v[0:1], v[2:3]
	s_nop 0
	v_add_f32_e32 v0, v0, v1
	v_fmamk_f32 v0, v0, 0x3a000000, v215
	v_cmp_gt_f32_e32 vcc, s90, v0
	v_mul_f32_e32 v1, 0x4f800000, v0
	s_nop 0
	v_cndmask_b32_e32 v0, v0, v1, vcc
	v_sqrt_f32_e32 v1, v0
	s_nop 0
	v_add_u32_e32 v2, -1, v1
	v_fma_f32 v3, -v2, v1, v0
	v_cmp_ge_f32_e64 s[42:43], 0, v3
	v_add_u32_e32 v3, 1, v1
	s_nop 0
	v_cndmask_b32_e64 v2, v1, v2, s[42:43]
	v_fma_f32 v1, -v3, v1, v0
	v_cmp_lt_f32_e64 s[42:43], 0, v1
	s_nop 1
	v_cndmask_b32_e64 v1, v2, v3, s[42:43]
	v_mul_f32_e32 v2, 0x37800000, v1
	v_cndmask_b32_e32 v1, v1, v2, vcc
	v_cmp_class_f32_e32 vcc, v0, v216
	s_nop 1
	v_cndmask_b32_e32 v0, v1, v0, vcc
	v_div_scale_f32 v1, s[14:15], v0, v0, 1.0
	v_rcp_f32_e32 v2, v1
	s_add_u32 s14, s56, s11
	s_addc_u32 s15, s57, s12
	v_lshl_add_u64 v[8:9], v[28:29], 2, s[14:15]
	v_fma_f32 v3, -v1, v2, 1.0
	v_fmac_f32_e32 v2, v3, v2
	v_div_scale_f32 v3, vcc, 1.0, v0, 1.0
	v_mul_f32_e32 v4, v3, v2
	v_fma_f32 v5, -v1, v4, v3
	v_fmac_f32_e32 v4, v5, v2
	v_fma_f32 v1, -v1, v4, v3
	v_div_fmas_f32 v1, v1, v2, v4
	v_add_co_u32_e32 v8, vcc, s89, v8
	v_div_fixup_f32 v12, v1, v0, 1.0
	s_nop 0
	v_addc_co_u32_e32 v9, vcc, 0, v9, vcc
	v_pk_mul_f32 v[14:15], v[104:105], v[12:13] op_sel_hi:[1,0]
	v_pk_mul_f32 v[12:13], v[102:103], v[12:13] op_sel_hi:[1,0]
	s_add_i32 s6, s6, s48
	s_cmpk_gt_i32 s6, 0x7f
	s_waitcnt vmcnt(1)
	v_pk_mul_f32 v[0:1], v[228:229], v[12:13]
	v_pk_mul_f32 v[2:3], v[230:231], v[14:15]
	s_waitcnt vmcnt(0)
	v_pk_add_f32 v[10:11], v[234:235], 1.0 op_sel_hi:[1,0]
	v_pk_add_f32 v[8:9], v[232:233], 1.0 op_sel_hi:[1,0]
	v_pk_fma_f32 v[2:3], v[10:11], v[2:3], v[226:227]
	v_pk_fma_f32 v[0:1], v[8:9], v[0:1], v[224:225]
	s_nop 0
	v_cvt_pk_bf16_f32 v0, v0, v1
	v_cvt_pk_bf16_f32 v1, v2, v3
	v_lshl_add_u64 v[2:3], s[26:27], 0, v[100:101]
	v_lshl_add_u64 v[100:101], v[100:101], 0, s[72:73]
	global_store_dwordx2 v[2:3], v[0:1], off
	s_cbranch_scc1 .LBB0_2222
.LBB0_2208:
	s_add_i32 s98, s6, 4
	s_mul_hi_i32 s99, s98, 0x48000
	s_mul_i32 s98, s98, 0x48000
	s_add_u32 s100, s56, s98
	s_addc_u32 s101, s57, s99
	v_lshl_add_u64 v[236:237], v[28:29], 2, s[100:101]
	global_load_dwordx4 v[224:227], v[236:237], off
	global_load_dwordx4 v[228:231], v[30:31], off
	s_add_u32 s100, s100, s89
	s_addc_u32 s101, s101, 0
	v_lshl_add_u64 v[238:239], v[28:29], 2, s[100:101]
	global_load_dwordx4 v[232:235], v[238:239], off
	v_lshl_add_u64 v[106:107], s[44:45], 0, v[100:101]
	global_load_dwordx2 v[0:1], v[106:107], off
	s_andn2_b64 vcc, exec, s[58:59]
	s_waitcnt vmcnt(0)
	v_cvt_f32_f16_e32 v102, v0
	v_cvt_f32_f16_e32 v104, v1
	v_cvt_f32_f16_sdwa v105, v1 dst_sel:DWORD dst_unused:UNUSED_PAD src0_sel:WORD_1
	v_cvt_f32_f16_sdwa v103, v0 dst_sel:DWORD dst_unused:UNUSED_PAD src0_sel:WORD_1
	s_cbranch_vccnz .LBB0_2220
	v_add_co_u32_e32 v0, vcc, 0xffa00000, v98
	v_mov_b32_e32 v8, 0
	s_nop 0
	v_addc_co_u32_e32 v1, vcc, -1, v99, vcc
	v_add_co_u32_e32 v4, vcc, 0xffb00000, v98
	v_mov_b32_e32 v12, 0
	s_nop 0
	v_addc_co_u32_e32 v5, vcc, -1, v99, vcc
	global_load_dwordx4 v[0:3], v[0:1], off
	s_nop 0
	global_load_dwordx4 v[4:7], v[4:5], off
	s_andn2_b64 vcc, exec, s[60:61]
	v_mov_b32_e32 v13, 0
	v_mov_b32_e32 v14, 0
	v_mov_b32_e32 v15, 0
	s_cbranch_vccnz .LBB0_2211
	v_add_co_u32_e32 v10, vcc, 0xffc00000, v98
	s_nop 1
	v_addc_co_u32_e32 v11, vcc, -1, v99, vcc
	global_load_dwordx4 v[12:15], v[10:11], off
